# v38 plus rwkvB step with preloaded LDS operands and interleaved MFMA chains; q-up units dealt from the top workgroups
# speedup vs baseline: 1.0010x; 1.0010x over previous
;     __device__ __forceinline__ bool next(int i, Unit& u) const {
;         const long L = (long)i * G + c; if (L >= nwg) return false;
;         int wgid = (int)L; { const int q = nwg / NXCD, r = nwg % NXCD, xcd = wgid % NXCD, off = wgid / NXCD; wgid = (xcd < r ? xcd * (q + 1) : r * (q + 1) + (xcd - r) * q) + off; }
;         const int nig = WGM * nN, gid = wgid / nig, fm = gid * WGM, gsz = (nM - fm) < WGM ? (nM - fm) : WGM;
;         u.pm = fm + ((wgid % nig) % gsz); u.pn = (wgid % nig) / gsz; return true;
; __global__ void __launch_bounds__(NTHREADS, 2) fwd_kernel(Args args) {
;     ...
;                 pg8::Gemm g{(const bf16_t*)(ws + WS_QL), (const bf16_t*)(ws + WS_WUQ) + (size_t)l * 1536 * 512, MROWS, 1536, 512, 512, 512};
;                 pg8::StaticOrder S; S.init(MROWS, 1536, F.nb, F.bid);
;                 pg8::EpiBf16<0> E{(bf16_t*)(ws + WS_Q), 1536};
;                 pg8::gemm_phase(F.lds, g, S, E, F.tid);
.LBB0_592:
	v_readlane_b32 s4, v253, 0
	v_readlane_b32 s16, v253, 12
	v_readlane_b32 s17, v253, 13
	v_mbcnt_lo_u32_b32 v129, -1, 0
	v_mbcnt_hi_u32_b32 v129, -1, v129
	v_readlane_b32 s5, v253, 1
	v_readlane_b32 s6, v253, 2
	v_readlane_b32 s7, v253, 3
	v_readlane_b32 s8, v253, 4
	v_readlane_b32 s9, v253, 5
	v_readlane_b32 s10, v253, 6
	v_readlane_b32 s11, v253, 7
	v_readlane_b32 s12, v253, 8
	v_readlane_b32 s13, v253, 9
	v_readlane_b32 s14, v253, 10
	v_readlane_b32 s15, v253, 11
	v_readlane_b32 s18, v253, 14
	v_readlane_b32 s19, v253, 15
	v_lshl_add_u32 v0, s82, 6, v129
	v_writelane_b32 v253, s4, 0
	s_mov_b32 s28, 8
	s_sub_i32 s96, s84, s96
	s_add_i32 s96, s96, -1
	s_cmpk_gt_i32 s96, 0xc5
	v_writelane_b32 v253, s5, 1
	v_writelane_b32 v253, s6, 2
	v_writelane_b32 v253, s7, 3
	v_writelane_b32 v253, s8, 4
	v_writelane_b32 v253, s9, 5
	v_writelane_b32 v253, s10, 6
	v_writelane_b32 v253, s11, 7
	v_writelane_b32 v253, s12, 8
	v_writelane_b32 v253, s13, 9
	v_writelane_b32 v253, s14, 10
	v_writelane_b32 v253, s15, 11
	v_writelane_b32 v253, s16, 12
	v_writelane_b32 v253, s17, 13
	v_writelane_b32 v253, s18, 14
	v_writelane_b32 v253, s19, 15
	v_readfirstlane_b32 s5, v0
	s_cbranch_scc1 .LBB0_618
	s_ashr_i32 s29, s96, 31
	s_lshr_b32 s0, s29, 29
	s_add_i32 s7, s96, s0
	s_and_b32 s0, s7, -8
	s_sub_i32 s6, s96, s0
	s_cmp_gt_i32 s6, 5
	s_mov_b64 s[0:1], -1
	s_cbranch_scc0 .LBB0_595
	s_mul_i32 s0, s6, 24
	s_or_b32 s4, s0, 6
	s_mov_b64 s[0:1], 0

;     __device__ __forceinline__ bool next(int i, Unit& u) const {
;         const long L = (long)i * G + c; if (L >= nwg) return false;
; __global__ void __launch_bounds__(NTHREADS, 2) fwd_kernel(Args args) {
;     ...
;             {
;                 pg8::Gemm g{(const bf16_t*)(ws + WS_KVL), (const bf16_t*)(ws + WS_WUKV) + (size_t)l * 2048 * 256, MROWS, 2048, 256, 256, 256};
;                 pg8::StaticOrder S; S.init(MROWS, 2048, F.nb, F.bid);
.LBB0_618:
	s_sub_i32 s96, s84, s96
	s_add_i32 s96, s96, -1
	v_readlane_b32 s4, v253, 0
	v_readlane_b32 s16, v253, 12
	v_readlane_b32 s17, v253, 13
	v_mbcnt_lo_u32_b32 v129, -1, 0
	v_mbcnt_hi_u32_b32 v129, -1, v129
	v_readlane_b32 s5, v253, 1
	v_readlane_b32 s6, v253, 2
	v_readlane_b32 s7, v253, 3
	v_readlane_b32 s8, v253, 4
	v_readlane_b32 s9, v253, 5
	v_readlane_b32 s10, v253, 6
	v_readlane_b32 s11, v253, 7
	v_readlane_b32 s12, v253, 8
	v_readlane_b32 s13, v253, 9
	v_readlane_b32 s14, v253, 10
	v_readlane_b32 s15, v253, 11
	v_readlane_b32 s18, v253, 14
	v_readlane_b32 s19, v253, 15
	v_lshl_add_u32 v0, s82, 6, v129
	v_writelane_b32 v253, s4, 0
	s_mov_b32 s30, 4
	s_cmpk_gt_i32 s96, 0x107
	v_writelane_b32 v253, s5, 1
	v_writelane_b32 v253, s6, 2
	v_writelane_b32 v253, s7, 3
	v_writelane_b32 v253, s8, 4
	v_writelane_b32 v253, s9, 5
	v_writelane_b32 v253, s10, 6
	v_writelane_b32 v253, s11, 7
	v_writelane_b32 v253, s12, 8
	v_writelane_b32 v253, s13, 9
	v_writelane_b32 v253, s14, 10
	v_writelane_b32 v253, s15, 11
	v_writelane_b32 v253, s16, 12
	v_writelane_b32 v253, s17, 13
	v_writelane_b32 v253, s18, 14
	v_writelane_b32 v253, s19, 15
	v_readfirstlane_b32 s5, v0
	s_cbranch_scc1 .LBB0_636
; __device__ __forceinline__ f32x4 zero4v() { f32x4 z = (f32x4){0.f, 0.f, 0.f, 0.f}; asm volatile("" : "+v"(z)); return z; }
; #define PG8_STAGE(bufoff, gbase, voff) do { _Pragma("unroll") for (int _i = 0; _i < 2; ++_i) \
;         __builtin_amdgcn_global_load_lds((const unsigned*)((const char*)(gbase) + (voff)[_i]), (LAS unsigned*)(lds + (bufoff) + ldsw + _i * 8192), 16, 0, 0); } while (0)
; #define PG8_WAIT_V(n) asm volatile("s_waitcnt vmcnt(" #n ")" ::: "memory")
; #define PG8_BAR __builtin_amdgcn_s_barrier()
;     const int wid = __builtin_amdgcn_readfirstlane(tid >> 6), lane = tid & 63, wr = wid >> 2, wc = wid & 3, fr = lane & 15, fq = lane >> 4;
;     int nt = g.K / BK; asm volatile("" : "+s"(nt));
;     unsigned voffA[2], voffB[2];
; #pragma unroll
;     for (int i = 0; i < 2; ++i) { int R, C; stage_rc(tid * 16 + i * 8192, R, C); const int Rb = Epi::PERM ? ((R & ~31) + perm32(R & 31)) : R;
;         voffA[i] = (unsigned)(R * g.lda + C) * 2u; voffB[i] = (unsigned)(Rb * g.ldb + C) * 2u; }
;     const size_t kstep = (size_t)(BK * 2);
;     const size_t hstepA = (size_t)HALF * g.lda * 2, hstepB = (size_t)HALF * g.ldb * 2;
;     const size_t tstepA = g.pstepA < 0 ? 2 * hstepA : (size_t)g.pstepA, tstepB = g.pstepB < 0 ? 2 * hstepB : (size_t)g.pstepB, qB = (size_t)g.qstepB;
;     const unsigned ldsw = (unsigned)wid * 1024u;
;     const int aoff = lds_byte(wr * 64 + fr, fq * 8), boff = lds_byte(wc * 32 + fr, fq * 8);
;     ...
;     Unit cur, nxt; int ui = 0;
;     if (!S.next(0, cur)) return;
;     f32x4 acc[2][2][4][2];
; #pragma unroll
;     for (int a = 0; a < 2; ++a)
; #pragma unroll
;         for (int b = 0; b < 2; ++b)
; #pragma unroll
;             for (int m = 0; m < 4; ++m)
; #pragma unroll
;                 for (int n = 0; n < 2; ++n) acc[a][b][m][n] = zero4v();
;     bf16x8 At[4][2], B0[2][2], B1[2][2];
;     const char* cA = (const char*)g.A + (size_t)cur.pm * tstepA; const char* cB = (const char*)g.Bt + (size_t)cur.pn * tstepB + (size_t)cur.pm * qB;
;     PG8_STAGE(PG8_SB(0, 0), cB, voffB); PG8_STAGE(PG8_SB(0, 1), cB + hstepB, voffB); PG8_STAGE(PG8_SA(0, 0), cA, voffA); PG8_STAGE(PG8_SA(0, 1), cA + hstepA, voffA);
;     if (wr == 1) PG8_BAR;
;     PG8_WAIT_V(2); PG8_BAR;
;     PG8_STAGE(PG8_SB(1, 0), cB + kstep, voffB); PG8_STAGE(PG8_SA(1, 0), cA + kstep, voffA); PG8_STAGE(PG8_SB(1, 1), cB + hstepB + kstep, voffB);
;     PG8_WAIT_V(6); PG8_BAR;
	v_lshlrev_b32_e32 v1, 4, v0
	v_add_u32_e32 v2, 0x2000, v1
	v_ashrrev_i32_e32 v3, 31, v2
	v_lshrrev_b32_e32 v3, 22, v3
	v_add_u32_e32 v3, v2, v3
	v_ashrrev_i32_e32 v150, 10, v3
	v_mul_i32_i24_e32 v3, 0x400, v150
	v_sub_u32_e32 v2, v2, v3
	v_lshrrev_b32_e32 v3, 4, v2
	v_bitop3_b32 v2, v3, v2, 32 bitop3:0x6c
	s_lshl_b64 s[0:1], s[92:93], 20
	v_ashrrev_i32_e32 v3, 31, v2
	s_add_u32 s31, s80, 0x4df04000
	v_lshrrev_b32_e32 v3, 26, v3
	s_addc_u32 s34, s81, 0
	v_add_u32_e32 v3, v2, v3
	s_waitcnt vmcnt(0) lgkmcnt(0)
	v_lshlrev_b32_e32 v4, 3, v150
	s_add_u32 s0, s80, s0
	v_ashrrev_i32_e32 v151, 6, v3
	v_and_b32_e32 v4, -16, v4
	s_addc_u32 s1, s81, s1
	v_add_u32_e32 v4, v151, v4
	s_add_u32 s35, s0, 0x36a24000
	v_and_b32_e32 v5, 3, v151
	s_mov_b32 s0, 0x7fffe0
	v_lshrrev_b32_e32 v6, 2, v4
	v_lshlrev_b32_e32 v7, 1, v4
	v_and_b32_e32 v3, 0xc0, v3
	v_and_or_b32 v5, v4, s0, v5
	v_and_b32_e32 v6, 4, v6
	v_and_b32_e32 v7, 24, v7
	v_sub_u32_e32 v2, v2, v3
	v_or3_b32 v5, v5, v6, v7
	v_lshlrev_b32_e32 v6, 5, v150
	v_ashrrev_i16_sdwa v2, v217, sext(v2) dst_sel:DWORD dst_unused:UNUSED_PAD src0_sel:DWORD src1_sel:BYTE_0
	v_and_b32_e32 v6, 32, v6
	v_bfe_i32 v152, v2, 0, 16
	v_add_lshl_u32 v2, v6, v152, 1
	v_lshl_add_u32 v130, v5, 9, v2
	v_lshl_add_u32 v136, v4, 9, v2
	v_bfe_i32 v2, v0, 27, 1
	v_lshrrev_b32_e32 v2, 22, v2
	v_add_u32_e32 v2, v1, v2
	v_and_b32_e32 v2, 0xfffffc00, v2
	v_sub_u32_e32 v1, v1, v2
	v_lshrrev_b32_e32 v2, 4, v1
	v_ashrrev_i32_e32 v3, 31, v0
	v_bitop3_b32 v1, v2, v1, 32 bitop3:0x6c
	v_lshrrev_b32_e32 v3, 26, v3
	v_ashrrev_i32_e32 v2, 31, v1
	v_add_u32_e32 v0, v0, v3
	v_lshrrev_b32_e32 v2, 26, v2
	v_ashrrev_i32_e32 v154, 6, v0
	v_add_u32_e32 v2, v1, v2
	v_lshlrev_b32_e32 v0, 3, v154
	v_ashrrev_i32_e32 v153, 6, v2
	v_and_b32_e32 v0, -16, v0
	s_addc_u32 s36, s1, 0
	v_add_u32_e32 v0, v153, v0
	v_and_b32_e32 v3, 3, v153
	s_ashr_i32 s38, s96, 31
	v_and_or_b32 v3, v0, s0, v3
	s_lshr_b32 s0, s38, 29
	s_add_i32 s0, s96, s0
	s_ashr_i32 s10, s5, 6
	s_ashr_i32 s1, s0, 3
	s_and_b32 s0, s0, -8
	s_ashr_i32 s11, s5, 8
	s_lshl_b32 s37, s10, 10
	s_sub_i32 s0, s96, s0
	s_cmp_lt_i32 s0, 0
	s_cselect_b32 s4, 34, 33
	s_mul_i32 s0, s0, s4
	s_add_i32 s0, s0, s1
	s_ashr_i32 s1, s0, 31
	s_lshr_b32 s1, s1, 27
	v_lshrrev_b32_e32 v4, 2, v0
	v_lshlrev_b32_e32 v5, 1, v0
	v_and_b32_e32 v2, 0xc0, v2
	s_add_i32 s1, s0, s1
	v_and_b32_e32 v4, 4, v4
	v_and_b32_e32 v5, 24, v5
	v_sub_u32_e32 v1, v1, v2
	s_ashr_i32 s4, s1, 5
	v_or3_b32 v3, v3, v4, v5
	v_lshlrev_b32_e32 v4, 5, v154
	v_ashrrev_i16_sdwa v1, v217, sext(v1) dst_sel:DWORD dst_unused:UNUSED_PAD src0_sel:DWORD src1_sel:BYTE_0
	s_lshl_b32 s6, s4, 2
	v_and_b32_e32 v4, 32, v4
	v_bfe_i32 v155, v1, 0, 16
	s_sub_i32 s4, 33, s6
	v_add_lshl_u32 v1, v4, v155, 1
	s_min_u32 s7, s4, 4
	s_andn2_b32 s1, s1, 31
	v_lshl_add_u32 v138, v3, 9, v1
	s_sub_i32 s8, s0, s1
	v_cvt_f32_ubyte0_e32 v3, s7
	v_cvt_f32_i32_e32 v2, s8
	v_rcp_iflag_f32_e32 v4, v3
	v_lshl_add_u32 v140, v0, 9, v1
	s_ashr_i32 s0, s8, 30
	s_or_b32 s4, s0, 1
	v_mul_f32_e32 v0, v2, v4
	v_trunc_f32_e32 v0, v0
	v_fma_f32 v1, -v0, v3, v2
	v_cvt_i32_f32_e32 v0, v0
	v_cmp_ge_f32_e64 s[0:1], |v1|, v3
	s_and_b64 s[0:1], s[0:1], exec
	s_cselect_b32 s0, s4, 0
	v_readfirstlane_b32 s1, v0
	s_add_i32 s4, s1, s0
	s_mul_i32 s0, s4, s7
	s_sub_i32 s0, s8, s0
	s_sext_i32_i8 s0, s0
	s_add_i32 s22, s6, s0
	s_ashr_i32 s23, s22, 31
	s_bfe_i64 s[6:7], s[4:5], 0x80000
	s_lshl_b64 s[0:1], s[22:23], 17
	s_lshl_b64 s[6:7], s[6:7], 17
	s_add_u32 s24, s35, s6
	v_mov_b64_e32 v[104:105], v[132:133]
	v_mov_b64_e32 v[108:109], v[132:133]
	v_mov_b64_e32 v[80:81], v[132:133]
	v_mov_b64_e32 v[84:85], v[132:133]
	v_mov_b64_e32 v[48:49], v[132:133]
	v_mov_b64_e32 v[56:57], v[132:133]
	v_mov_b64_e32 v[24:25], v[132:133]
	v_mov_b64_e32 v[32:33], v[132:133]
	v_mov_b64_e32 v[120:121], v[132:133]
	v_mov_b64_e32 v[124:125], v[132:133]
	v_mov_b64_e32 v[112:113], v[132:133]
	v_mov_b64_e32 v[116:117], v[132:133]
	v_mov_b64_e32 v[88:89], v[132:133]
	v_mov_b64_e32 v[96:97], v[132:133]
	v_mov_b64_e32 v[64:65], v[132:133]
	v_mov_b64_e32 v[72:73], v[132:133]
	v_mov_b64_e32 v[52:53], v[132:133]
	v_mov_b64_e32 v[60:61], v[132:133]
	v_mov_b64_e32 v[28:29], v[132:133]
	v_mov_b64_e32 v[36:37], v[132:133]
	v_mov_b64_e32 v[8:9], v[132:133]
	v_mov_b64_e32 v[12:13], v[132:133]
	v_mov_b64_e32 v[0:1], v[132:133]
	v_mov_b64_e32 v[4:5], v[132:133]
	v_mov_b64_e32 v[92:93], v[132:133]
	v_mov_b64_e32 v[100:101], v[132:133]
	v_mov_b64_e32 v[68:69], v[132:133]
	v_mov_b64_e32 v[76:77], v[132:133]
	v_mov_b64_e32 v[40:41], v[132:133]
	v_mov_b64_e32 v[44:45], v[132:133]
	v_mov_b64_e32 v[16:17], v[132:133]
	v_mov_b64_e32 v[20:21], v[132:133]
	s_addc_u32 s25, s36, s7
	s_add_i32 s39, s37, 0
	v_mov_b64_e32 v[106:107], v[134:135]
	v_mov_b64_e32 v[110:111], v[134:135]
	v_mov_b64_e32 v[82:83], v[134:135]
	v_mov_b64_e32 v[86:87], v[134:135]
	v_mov_b64_e32 v[50:51], v[134:135]
	v_mov_b64_e32 v[58:59], v[134:135]
	v_mov_b64_e32 v[26:27], v[134:135]
	v_mov_b64_e32 v[34:35], v[134:135]
	v_mov_b64_e32 v[122:123], v[134:135]
	v_mov_b64_e32 v[126:127], v[134:135]
	v_mov_b64_e32 v[114:115], v[134:135]
	v_mov_b64_e32 v[118:119], v[134:135]
	v_mov_b64_e32 v[90:91], v[134:135]
	v_mov_b64_e32 v[98:99], v[134:135]
	v_mov_b64_e32 v[66:67], v[134:135]
	v_mov_b64_e32 v[74:75], v[134:135]
	v_mov_b64_e32 v[54:55], v[134:135]
	v_mov_b64_e32 v[62:63], v[134:135]
	v_mov_b64_e32 v[30:31], v[134:135]
	v_mov_b64_e32 v[38:39], v[134:135]
	v_mov_b64_e32 v[10:11], v[134:135]
	v_mov_b64_e32 v[14:15], v[134:135]
	v_mov_b64_e32 v[2:3], v[134:135]
	v_mov_b64_e32 v[6:7], v[134:135]
	v_mov_b64_e32 v[94:95], v[134:135]
	v_mov_b64_e32 v[102:103], v[134:135]
	v_mov_b64_e32 v[70:71], v[134:135]
	v_mov_b64_e32 v[78:79], v[134:135]
	v_mov_b64_e32 v[42:43], v[134:135]
	v_mov_b64_e32 v[46:47], v[134:135]
	v_mov_b64_e32 v[18:19], v[134:135]
	v_mov_b64_e32 v[22:23], v[134:135]
	s_add_i32 m0, s39, 0x10000
	s_nop 0
	global_load_lds_dwordx4 v138, s[24:25]
	s_add_i32 m0, s39, 0x12000
	s_add_u32 s6, s24, 0x10000
	global_load_lds_dwordx4 v130, s[24:25]
	s_addc_u32 s7, s25, 0
	s_add_i32 m0, s39, 0x14000
	v_mov_b32_e32 v139, v128
	global_load_lds_dwordx4 v138, s[6:7]
	s_add_i32 m0, s39, 0x16000
	s_add_u32 s26, s31, s0
	s_addc_u32 s27, s34, s1
	s_add_i32 s40, s39, 0x2000
	global_load_lds_dwordx4 v130, s[6:7]
	s_mov_b32 m0, s39
	s_add_u32 s0, s26, 0x10000
	global_load_lds_dwordx4 v140, s[26:27]
	s_mov_b32 m0, s40
	s_addc_u32 s1, s27, 0
	s_add_i32 s41, s39, 0x4000
	global_load_lds_dwordx4 v136, s[26:27]
	s_mov_b32 m0, s41
	s_add_i32 s42, s39, 0x6000
	global_load_lds_dwordx4 v140, s[0:1]
	s_mov_b32 m0, s42
	v_mov_b32_e32 v131, v128
	global_load_lds_dwordx4 v136, s[0:1]
	v_mov_b32_e32 v141, v128
	v_mov_b32_e32 v137, v128
	s_cmp_eq_u32 s11, 1
	v_lshl_add_u64 v[148:149], s[24:25], 0, v[138:139]
	v_lshl_add_u64 v[146:147], s[24:25], 0, v[130:131]
	v_lshl_add_u64 v[142:143], s[26:27], 0, v[140:141]
	s_cselect_b64 s[0:1], -1, 0
	s_cmp_lg_u32 s11, 1
	v_lshl_add_u64 v[144:145], s[26:27], 0, v[136:137]
	s_cbranch_scc1 .LBB0_621
	s_barrier

; #define LAS __attribute__((address_space(3)))
; __device__ __forceinline__ unsigned cvt_pk_bf16(float lo, float hi) { return __builtin_bit_cast(unsigned, __builtin_convertvector((f32x2){lo, hi}, bf16x2n)); }
; __device__ __forceinline__ float bf2f(bf16_t h) { return __uint_as_float(((unsigned)h) << 16); }
; #define MFMA_BF(a, b, c) __builtin_amdgcn_mfma_f32_16x16x32_bf16(a, b, c, 0, 0, 0)
; __device__ __forceinline__ void rwkvB_phase(const Frame& F) {
;     ...
;             const LAS unsigned char* sb = F.lds + (c & 3) * RB_SLOT;
;             bf16_t* Sg = SC + (size_t)(hd * CH_NCH + c) * 4096 + (16 * vt + qi) * 64 + 4 * g;
;             bf16x8 bh[2], bl[2];
; #pragma unroll
;             for (int ks = 0; ks < 2; ++ks) {
;                 u32x4 wh, wl;
; #pragma unroll
;                 for (int h = 0; h < 2; ++h) {
;                     const f32x4 x = T[2 * ks + h];
;                     float xh[4];
; #pragma unroll
;                     for (int j = 0; j < 4; ++j) xh[j] = bf2f(f2bf(x[j]));
;                     const unsigned h0 = cvt_pk_bf16(xh[0], xh[1]), h1 = cvt_pk_bf16(xh[2], xh[3]);
;                     const unsigned l0 = cvt_pk_bf16(x[0] - xh[0], x[1] - xh[1]), l1 = cvt_pk_bf16(x[2] - xh[2], x[3] - xh[3]);
;                     if (h == 0) { wh.x = h0; wh.y = h1; wl.x = l0; wl.y = l1; } else { wh.z = h0; wh.w = h1; wl.z = l0; wl.w = l1; }
;                     u32x2 sv; sv.x = h0; sv.y = h1; *(u32x2*)(Sg + 16 * (2 * ks + h)) = sv;
;                 }
;                 bh[ks] = __builtin_bit_cast(bf16x8, wh); bl[ks] = __builtin_bit_cast(bf16x8, wl);
;             }
; #pragma unroll
;             for (int kt = 0; kt < 4; ++kt) {
;                 f32x4 acc = *(const LAS f32x4*)(sb + 16384 + ((16 * vt + qi) * 64 + 16 * kt + 4 * g) * 4);
; #pragma unroll
;                 for (int ks = 0; ks < 2; ++ks) {
;                     const bf16x8 ah = *(const LAS bf16x8*)(sb + ((16 * kt + qi) * 64 + 32 * ks + 8 * g) * 2);
;                     const bf16x8 al = *(const LAS bf16x8*)(sb + 8192 + ((16 * kt + qi) * 64 + 32 * ks + 8 * g) * 2);
;                     acc = MFMA_BF(ah, bh[ks], acc); acc = MFMA_BF(ah, bl[ks], acc); acc = MFMA_BF(al, bh[ks], acc);
;                 }
;                 T[kt] = acc;
;             }
.LBB0_848:
	s_mov_b64 s[2:3], -1
	s_and_b64 vcc, exec, s[0:1]
	s_cbranch_vccz .LBB0_850
	s_add_i32 s2, s5, 0xfffe8000
	s_and_b32 s6, s2, 0x18000
	v_add_u32_e32 v64, s6, v51
	v_add_u32_e32 v65, s6, v50
	ds_read_b128 v[80:83], v65 offset:16384
	ds_read_b128 v[110:113], v65 offset:16448
	ds_read_b128 v[122:125], v65 offset:16512
	ds_read_b128 v[152:155], v65 offset:16576
	ds_read_b128 v[156:159], v64
	ds_read_b128 v[160:163], v64 offset:2048
	ds_read_b128 v[164:167], v64 offset:4096
	ds_read_b128 v[184:187], v64 offset:6144
	ds_read_b128 v[188:191], v64 offset:8192
	ds_read_b128 v[202:205], v64 offset:10240
	ds_read_b128 v[206:209], v64 offset:12288
	ds_read_b128 v[210:213], v64 offset:14336
	ds_read_b128 v[220:223], v64 offset:64
	ds_read_b128 v[230:233], v64 offset:2112
	ds_read_b128 v[234:237], v64 offset:4160
	ds_read_b128 v[238:241], v64 offset:6208
	ds_read_b128 v[242:245], v64 offset:8256
	ds_read_b128 v[246:249], v64 offset:10304
	v_cvt_pk_bf16_f32 v16, v4, v5
	v_and_b32_e32 v17, 0xffff0000, v16
	v_lshlrev_b32_e32 v16, 16, v16
	v_cvt_pk_bf16_f32 v20, v16, v17
	v_pk_add_f32 v[28:29], v[4:5], v[16:17] neg_lo:[0,1] neg_hi:[0,1]
	v_cvt_pk_bf16_f32 v16, v6, v7
	s_mul_i32 s2, s96, 0x84
	v_and_b32_e32 v31, 0xffff0000, v16
	v_lshlrev_b32_e32 v30, 16, v16
	v_cvt_pk_bf16_f32 v16, v8, v9
	s_add_i32 s2, s2, s4
	v_and_b32_e32 v37, 0xffff0000, v16
	v_lshlrev_b32_e32 v36, 16, v16
	v_cvt_pk_bf16_f32 v16, v10, v11
	s_ashr_i32 s3, s2, 31
	v_and_b32_e32 v53, 0xffff0000, v16
	v_lshlrev_b32_e32 v52, 16, v16
	v_cvt_pk_bf16_f32 v16, v12, v13
	v_cvt_pk_bf16_f32 v17, v14, v15
	v_cvt_pk_bf16_f32 v18, v0, v1
	v_cvt_pk_bf16_f32 v19, v2, v3
	s_lshl_b64 s[2:3], s[2:3], 13
	v_and_b32_e32 v57, 0xffff0000, v16
	v_lshlrev_b32_e32 v56, 16, v16
	v_and_b32_e32 v59, 0xffff0000, v17
	v_lshlrev_b32_e32 v58, 16, v17
	v_and_b32_e32 v61, 0xffff0000, v18
	v_lshlrev_b32_e32 v60, 16, v18
	v_and_b32_e32 v63, 0xffff0000, v19
	v_lshlrev_b32_e32 v62, 16, v19
	v_lshl_add_u64 v[24:25], v[40:41], 0, s[2:3]
	v_cvt_pk_bf16_f32 v21, v30, v31
	v_cvt_pk_bf16_f32 v22, v36, v37
	v_cvt_pk_bf16_f32 v23, v52, v53
	v_cvt_pk_bf16_f32 v16, v56, v57
	v_cvt_pk_bf16_f32 v17, v58, v59
	v_cvt_pk_bf16_f32 v18, v60, v61
	v_cvt_pk_bf16_f32 v19, v62, v63
	flat_store_dwordx2 v[24:25], v[20:21]
	flat_store_dwordx2 v[24:25], v[22:23] offset:32
	flat_store_dwordx2 v[24:25], v[16:17] offset:64
	flat_store_dwordx2 v[24:25], v[18:19] offset:96
	v_pk_add_f32 v[30:31], v[6:7], v[30:31] neg_lo:[0,1] neg_hi:[0,1]
	v_cvt_pk_bf16_f32 v28, v28, v29
	v_cvt_pk_bf16_f32 v29, v30, v31
	v_pk_add_f32 v[30:31], v[8:9], v[36:37] neg_lo:[0,1] neg_hi:[0,1]
	v_pk_add_f32 v[52:53], v[10:11], v[52:53] neg_lo:[0,1] neg_hi:[0,1]
	v_cvt_pk_bf16_f32 v30, v30, v31
	v_cvt_pk_bf16_f32 v31, v52, v53
	v_add_f32_e64 v32, v12, -v56
	v_add_f32_e64 v33, v13, -v57
	v_pk_add_f32 v[36:37], v[0:1], v[60:61] neg_lo:[0,1] neg_hi:[0,1]
	v_cvt_pk_bf16_f32 v56, v32, v33
	v_pk_add_f32 v[32:33], v[14:15], v[58:59] neg_lo:[0,1] neg_hi:[0,1]
	v_cvt_pk_bf16_f32 v57, v32, v33
	v_cvt_pk_bf16_f32 v58, v36, v37
	v_pk_add_f32 v[36:37], v[2:3], v[62:63] neg_lo:[0,1] neg_hi:[0,1]
	v_cvt_pk_bf16_f32 v59, v36, v37
	ds_read_b128 v[52:55], v64 offset:12352
	ds_read_b128 v[60:63], v64 offset:14400
	s_waitcnt lgkmcnt(2)
	v_mfma_f32_16x16x32_bf16 v[24:27], v[156:159], v[20:23], v[80:83]
	v_mfma_f32_16x16x32_bf16 v[32:35], v[160:163], v[20:23], v[110:113]
	v_mfma_f32_16x16x32_bf16 v[36:39], v[164:167], v[20:23], v[122:125]
	v_mfma_f32_16x16x32_bf16 v[152:155], v[184:187], v[20:23], v[152:155]
	v_mfma_f32_16x16x32_bf16 v[24:27], v[156:159], v[28:31], v[24:27]
	v_mfma_f32_16x16x32_bf16 v[32:35], v[160:163], v[28:31], v[32:35]
	v_mfma_f32_16x16x32_bf16 v[36:39], v[164:167], v[28:31], v[36:39]
	v_mfma_f32_16x16x32_bf16 v[152:155], v[184:187], v[28:31], v[152:155]
	v_mfma_f32_16x16x32_bf16 v[24:27], v[188:191], v[20:23], v[24:27]
	v_mfma_f32_16x16x32_bf16 v[32:35], v[202:205], v[20:23], v[32:35]
	v_mfma_f32_16x16x32_bf16 v[36:39], v[206:209], v[20:23], v[36:39]
	v_mfma_f32_16x16x32_bf16 v[152:155], v[210:213], v[20:23], v[152:155]
	v_mfma_f32_16x16x32_bf16 v[24:27], v[220:223], v[16:19], v[24:27]
	v_mfma_f32_16x16x32_bf16 v[32:35], v[230:233], v[16:19], v[32:35]
	v_mfma_f32_16x16x32_bf16 v[36:39], v[234:237], v[16:19], v[36:39]
	v_mfma_f32_16x16x32_bf16 v[152:155], v[238:241], v[16:19], v[152:155]
	v_mfma_f32_16x16x32_bf16 v[24:27], v[220:223], v[56:59], v[24:27]
	v_mfma_f32_16x16x32_bf16 v[32:35], v[230:233], v[56:59], v[32:35]
	v_mfma_f32_16x16x32_bf16 v[36:39], v[234:237], v[56:59], v[36:39]
	v_mfma_f32_16x16x32_bf16 v[152:155], v[238:241], v[56:59], v[152:155]
	s_waitcnt lgkmcnt(0)
	v_mfma_f32_16x16x32_bf16 v[24:27], v[242:245], v[16:19], v[24:27]
	v_mfma_f32_16x16x32_bf16 v[32:35], v[246:249], v[16:19], v[32:35]
	v_mfma_f32_16x16x32_bf16 v[36:39], v[52:55], v[16:19], v[36:39]
	v_mfma_f32_16x16x32_bf16 v[16:19], v[60:63], v[16:19], v[152:155]
	s_mov_b64 s[2:3], 0
